# GLA recurrence: next kdec/decay prefetch loads issued at the step top instead of after the first MFMA group
# baseline (speedup 1.0000x reference)
; __device__ __forceinline__ void gla_item(LAS unsigned char* lds, int item, const bf16_t* KDT, const float* DEC, const bf16_t* GVT, const bf16_t* GQF, bf16_t* OG) {
;     ...
;     for (int c = 0; c < 30; c += 3) {
;         GLA_LOAD(s2, c + 2); GLA_STEP(s0, c);
;         GLA_LOAD(s0, c + 3); GLA_STEP(s1, c + 1);
;         GLA_LOAD(s1, c + 4); GLA_STEP(s2, c + 2);
;     }
.Lgla_loop:
	s_waitcnt vmcnt(11)
	global_load_dwordx4 v[40:43], v0, s[58:59]
	global_load_dwordx4 v[44:47], v0, s[58:59] offset:1024
	global_load_dwordx4 v[48:51], v1, s[60:61]
	s_add_u32 s58, s58, 0x4000
	s_addc_u32 s59, s59, 0
	s_add_u32 s60, s60, 0x200
	s_addc_u32 s61, s61, 0
	v_add_u32_e32 v5, s68, v0
	ds_read_b128 v[52:55], v5
	ds_read_b128 v[56:59], v5 offset:1024
	ds_read_b128 v[60:63], v5 offset:2048
	ds_read_b128 v[64:67], v5 offset:3072
	v_pk_mul_f32 v[8:9], v[8:9], v[24:25]
	v_pk_mul_f32 v[10:11], v[10:11], v[26:27]
	v_pk_mul_f32 v[12:13], v[12:13], v[24:25]
	v_pk_mul_f32 v[14:15], v[14:15], v[26:27]
	s_and_b32 s69, s54, 1
	s_mulk_i32 s69, 0x2200
	v_add_u32_e32 v6, s69, v3
	v_add_u32_e32 v7, s69, v4
	s_waitcnt lgkmcnt(0)
	s_nop 0
	v_mfma_f32_16x16x32_bf16 v[8:11], v[16:19], v[52:55], v[8:11]
	v_mfma_f32_16x16x32_bf16 v[12:15], v[16:19], v[60:63], v[12:15]
	v_mfma_f32_16x16x32_bf16 v[8:11], v[20:23], v[56:59], v[8:11]
	v_mfma_f32_16x16x32_bf16 v[12:15], v[20:23], v[64:67], v[12:15]
	s_nop 7
	v_cvt_pk_bf16_f32 v104, v8, v9
	v_cvt_pk_bf16_f32 v105, v10, v11
	v_cvt_pk_bf16_f32 v106, v12, v13
	v_cvt_pk_bf16_f32 v107, v14, v15
	ds_write_b64 v6, v[104:105]
	ds_write_b64 v6, v[106:107] offset:4352
	s_waitcnt vmcnt(11)
	s_waitcnt lgkmcnt(0)
	s_barrier
	v_add_u32_e32 v5, s68, v108
	ds_read_b128 v[68:71], v7
	ds_read_b128 v[72:75], v7 offset:64
	ds_read_b128 v[76:79], v7 offset:128
	ds_read_b128 v[80:83], v7 offset:192
	ds_read_b128 v[84:87], v5
	ds_read_b128 v[88:91], v5 offset:1024
	ds_read_b128 v[92:95], v5 offset:2048
	ds_read_b128 v[96:99], v5 offset:3072
	s_add_i32 s0, s68, 0xffffb000
	s_cmp_lg_u32 s68, 0x5000
	s_cselect_b32 s0, s0, 0x14000
	s_mov_b64 exec, s[36:37]
	s_add_i32 m0, s0, s55
	s_nop 0
	global_load_lds_dwordx4 v109, s[62:63]
	s_mov_b64 exec, -1
	s_add_i32 m0, s0, s53
	s_nop 0
	global_load_lds_dwordx4 v0, s[64:65]
	global_load_lds_dwordx4 v0, s[64:65] offset:1024
	s_add_u32 s62, s62, 0x1000
	s_addc_u32 s63, s63, 0
	s_add_u32 s64, s64, 0x4000
	s_addc_u32 s65, s65, 0
	s_waitcnt lgkmcnt(0)
	v_mfma_f32_16x16x32_bf16 v[100:103], v[68:71], v[84:87], 0
	v_mfma_f32_16x16x32_bf16 v[100:103], v[72:75], v[88:91], v[100:103]
	v_mfma_f32_16x16x32_bf16 v[100:103], v[76:79], v[92:95], v[100:103]
	v_mfma_f32_16x16x32_bf16 v[100:103], v[80:83], v[96:99], v[100:103]
	s_add_i32 s68, s68, 0x5000
	s_cmp_lg_u32 s68, 0x19000
	s_cselect_b32 s68, s68, 0x5000
	s_nop 7
	v_pk_mul_f32 v[100:101], v[100:101], s[22:23] op_sel_hi:[1,0]
	v_pk_mul_f32 v[102:103], v[102:103], s[22:23] op_sel_hi:[1,0]
	s_cmpk_lt_u32 s54, 0x20
	v_cvt_pk_bf16_f32 v104, v100, v101
	v_cvt_pk_bf16_f32 v105, v102, v103
	s_cbranch_scc0 .Lgla_nost0
	global_store_dwordx2 v2, v[104:105], s[66:67]
.Lgla_nost0:
	s_add_u32 s66, s66, 0x1000
	s_addc_u32 s67, s67, 0
	s_add_i32 s54, s54, 1
	s_waitcnt vmcnt(11)
	global_load_dwordx4 v[16:19], v0, s[58:59]
	global_load_dwordx4 v[20:23], v0, s[58:59] offset:1024
	global_load_dwordx4 v[24:27], v1, s[60:61]
	s_add_u32 s58, s58, 0x4000
	s_addc_u32 s59, s59, 0
	s_add_u32 s60, s60, 0x200
	s_addc_u32 s61, s61, 0
	v_add_u32_e32 v5, s68, v0
	ds_read_b128 v[52:55], v5
	ds_read_b128 v[56:59], v5 offset:1024
	ds_read_b128 v[60:63], v5 offset:2048
	ds_read_b128 v[64:67], v5 offset:3072
	v_pk_mul_f32 v[8:9], v[8:9], v[36:37]
	v_pk_mul_f32 v[10:11], v[10:11], v[38:39]
	v_pk_mul_f32 v[12:13], v[12:13], v[36:37]
	v_pk_mul_f32 v[14:15], v[14:15], v[38:39]
	s_and_b32 s69, s54, 1
	s_mulk_i32 s69, 0x2200
	v_add_u32_e32 v6, s69, v3
	v_add_u32_e32 v7, s69, v4
	s_waitcnt lgkmcnt(0)
	s_nop 0
	v_mfma_f32_16x16x32_bf16 v[8:11], v[28:31], v[52:55], v[8:11]
	v_mfma_f32_16x16x32_bf16 v[12:15], v[28:31], v[60:63], v[12:15]
	v_mfma_f32_16x16x32_bf16 v[8:11], v[32:35], v[56:59], v[8:11]
	v_mfma_f32_16x16x32_bf16 v[12:15], v[32:35], v[64:67], v[12:15]
	s_nop 7
	v_cvt_pk_bf16_f32 v104, v8, v9
	v_cvt_pk_bf16_f32 v105, v10, v11
	v_cvt_pk_bf16_f32 v106, v12, v13
	v_cvt_pk_bf16_f32 v107, v14, v15
	ds_write_b64 v6, v[104:105]
	ds_write_b64 v6, v[106:107] offset:4352
	s_waitcnt vmcnt(11)
	s_waitcnt lgkmcnt(0)
	s_barrier
	v_add_u32_e32 v5, s68, v108
	ds_read_b128 v[68:71], v7
	ds_read_b128 v[72:75], v7 offset:64
	ds_read_b128 v[76:79], v7 offset:128
	ds_read_b128 v[80:83], v7 offset:192
	ds_read_b128 v[84:87], v5
	ds_read_b128 v[88:91], v5 offset:1024
	ds_read_b128 v[92:95], v5 offset:2048
	ds_read_b128 v[96:99], v5 offset:3072
	s_add_i32 s0, s68, 0xffffb000
	s_cmp_lg_u32 s68, 0x5000
	s_cselect_b32 s0, s0, 0x14000
	s_mov_b64 exec, s[36:37]
	s_add_i32 m0, s0, s55
	s_nop 0
	global_load_lds_dwordx4 v109, s[62:63]
	s_mov_b64 exec, -1
	s_add_i32 m0, s0, s53
	s_nop 0
	global_load_lds_dwordx4 v0, s[64:65]
	global_load_lds_dwordx4 v0, s[64:65] offset:1024
	s_add_u32 s62, s62, 0x1000
	s_addc_u32 s63, s63, 0
	s_add_u32 s64, s64, 0x4000
	s_addc_u32 s65, s65, 0
	s_waitcnt lgkmcnt(0)
	v_mfma_f32_16x16x32_bf16 v[100:103], v[68:71], v[84:87], 0
	v_mfma_f32_16x16x32_bf16 v[100:103], v[72:75], v[88:91], v[100:103]
	v_mfma_f32_16x16x32_bf16 v[100:103], v[76:79], v[92:95], v[100:103]
	v_mfma_f32_16x16x32_bf16 v[100:103], v[80:83], v[96:99], v[100:103]
	s_add_i32 s68, s68, 0x5000
	s_cmp_lg_u32 s68, 0x19000
	s_cselect_b32 s68, s68, 0x5000
	s_nop 7
	v_pk_mul_f32 v[100:101], v[100:101], s[22:23] op_sel_hi:[1,0]
	v_pk_mul_f32 v[102:103], v[102:103], s[22:23] op_sel_hi:[1,0]
	s_cmpk_lt_u32 s54, 0x20
	v_cvt_pk_bf16_f32 v104, v100, v101
	v_cvt_pk_bf16_f32 v105, v102, v103
	s_cbranch_scc0 .Lgla_nost1
	global_store_dwordx2 v2, v[104:105], s[66:67]
; __device__ __forceinline__ void gla_item(LAS unsigned char* lds, int item, const bf16_t* KDT, const float* DEC, const bf16_t* GVT, const bf16_t* GQF, bf16_t* OG) {
;     ...
;     for (int c = 0; c < 30; c += 3) {
;         GLA_LOAD(s2, c + 2); GLA_STEP(s0, c);
;         GLA_LOAD(s0, c + 3); GLA_STEP(s1, c + 1);
;         GLA_LOAD(s1, c + 4); GLA_STEP(s2, c + 2);
;     }
.Lgla_nost1:
	s_add_u32 s66, s66, 0x1000
	s_addc_u32 s67, s67, 0
	s_add_i32 s54, s54, 1
	s_waitcnt vmcnt(11)
	global_load_dwordx4 v[28:31], v0, s[58:59]
	global_load_dwordx4 v[32:35], v0, s[58:59] offset:1024
	global_load_dwordx4 v[36:39], v1, s[60:61]
	s_add_u32 s58, s58, 0x4000
	s_addc_u32 s59, s59, 0
	s_add_u32 s60, s60, 0x200
	s_addc_u32 s61, s61, 0
	v_add_u32_e32 v5, s68, v0
	ds_read_b128 v[52:55], v5
	ds_read_b128 v[56:59], v5 offset:1024
	ds_read_b128 v[60:63], v5 offset:2048
	ds_read_b128 v[64:67], v5 offset:3072
	v_pk_mul_f32 v[8:9], v[8:9], v[48:49]
	v_pk_mul_f32 v[10:11], v[10:11], v[50:51]
	v_pk_mul_f32 v[12:13], v[12:13], v[48:49]
	v_pk_mul_f32 v[14:15], v[14:15], v[50:51]
	s_and_b32 s69, s54, 1
	s_mulk_i32 s69, 0x2200
	v_add_u32_e32 v6, s69, v3
	v_add_u32_e32 v7, s69, v4
	s_waitcnt lgkmcnt(0)
	s_nop 0
	v_mfma_f32_16x16x32_bf16 v[8:11], v[40:43], v[52:55], v[8:11]
	v_mfma_f32_16x16x32_bf16 v[12:15], v[40:43], v[60:63], v[12:15]
	v_mfma_f32_16x16x32_bf16 v[8:11], v[44:47], v[56:59], v[8:11]
	v_mfma_f32_16x16x32_bf16 v[12:15], v[44:47], v[64:67], v[12:15]
	s_nop 7
	v_cvt_pk_bf16_f32 v104, v8, v9
	v_cvt_pk_bf16_f32 v105, v10, v11
	v_cvt_pk_bf16_f32 v106, v12, v13
	v_cvt_pk_bf16_f32 v107, v14, v15
	ds_write_b64 v6, v[104:105]
	ds_write_b64 v6, v[106:107] offset:4352
	s_waitcnt vmcnt(11)
	s_waitcnt lgkmcnt(0)
	s_barrier
	v_add_u32_e32 v5, s68, v108
	ds_read_b128 v[68:71], v7
	ds_read_b128 v[72:75], v7 offset:64
	ds_read_b128 v[76:79], v7 offset:128
	ds_read_b128 v[80:83], v7 offset:192
	ds_read_b128 v[84:87], v5
	ds_read_b128 v[88:91], v5 offset:1024
	ds_read_b128 v[92:95], v5 offset:2048
	ds_read_b128 v[96:99], v5 offset:3072
	s_add_i32 s0, s68, 0xffffb000
	s_cmp_lg_u32 s68, 0x5000
	s_cselect_b32 s0, s0, 0x14000
	s_mov_b64 exec, s[36:37]
	s_add_i32 m0, s0, s55
	s_nop 0
	global_load_lds_dwordx4 v109, s[62:63]
	s_mov_b64 exec, -1
	s_add_i32 m0, s0, s53
	s_nop 0
	global_load_lds_dwordx4 v0, s[64:65]
	global_load_lds_dwordx4 v0, s[64:65] offset:1024
	s_add_u32 s62, s62, 0x1000
	s_addc_u32 s63, s63, 0
	s_add_u32 s64, s64, 0x4000
	s_addc_u32 s65, s65, 0
	s_waitcnt lgkmcnt(0)
	v_mfma_f32_16x16x32_bf16 v[100:103], v[68:71], v[84:87], 0
	v_mfma_f32_16x16x32_bf16 v[100:103], v[72:75], v[88:91], v[100:103]
	v_mfma_f32_16x16x32_bf16 v[100:103], v[76:79], v[92:95], v[100:103]
	v_mfma_f32_16x16x32_bf16 v[100:103], v[80:83], v[96:99], v[100:103]
	s_add_i32 s68, s68, 0x5000
	s_cmp_lg_u32 s68, 0x19000
	s_cselect_b32 s68, s68, 0x5000
	s_nop 7
	v_pk_mul_f32 v[100:101], v[100:101], s[22:23] op_sel_hi:[1,0]
	v_pk_mul_f32 v[102:103], v[102:103], s[22:23] op_sel_hi:[1,0]
	s_cmpk_lt_u32 s54, 0x20
	v_cvt_pk_bf16_f32 v104, v100, v101
	v_cvt_pk_bf16_f32 v105, v102, v103
	s_cbranch_scc0 .Lgla_nost2
	global_store_dwordx2 v2, v[104:105], s[66:67]
